# mixer residual epilogue no longer stores a separate bf16 copy of x (FFN-down epilogue rebuilds x from the stored GEMM operand A'=bf16(x*gm) times 1/gm in f32): same bf16-width storage of the stream, 6
# speedup vs baseline: 1.0082x; 1.0082x over previous
.LBB0_1058:
	v_lshlrev_b64 v[216:217], 11, v[178:179]
	v_lshl_add_u64 v[182:183], v[216:217], 0, v[196:197]
	s_waitcnt vmcnt(0) lgkmcnt(0)
	v_pk_fma_f32 v[192:193], v[142:143], v[110:111], v[170:171]
	v_lshlrev_b64 v[142:143], 1, v[182:183]
	v_pk_fma_f32 v[190:191], v[144:145], v[112:113], v[172:173]
	v_pk_fma_f32 v[174:175], v[138:139], v[106:107], v[174:175]
	v_cvt_pk_bf16_f32 v138, v192, v193
	v_cvt_pk_bf16_f32 v139, v190, v191
	v_lshl_add_u64 v[144:145], s[12:13], 0, v[142:143]
	v_pk_fma_f32 v[176:177], v[140:141], v[108:109], v[176:177]
	v_cvt_pk_bf16_f32 v140, v174, v175
	v_lshl_add_u64 v[142:143], s[18:19], 0, v[142:143]
	v_cvt_pk_bf16_f32 v141, v176, v177
	v_lshlrev_b64 v[218:219], 11, v[200:201]
	v_pk_mul_f32 v[144:145], v[100:101], v[176:177]
	v_pk_mul_f32 v[138:139], v[102:103], v[192:193]
	v_pk_mul_f32 v[140:141], v[104:105], v[190:191]
	v_cvt_pk_bf16_f32 v138, v138, v139
	v_pk_mul_f32 v[170:171], v[98:99], v[174:175]
	v_cvt_pk_bf16_f32 v139, v140, v141
	v_pk_fma_f32 v[172:173], v[134:135], v[110:111], v[162:163]
	v_cvt_pk_bf16_f32 v140, v170, v171
	v_cvt_pk_bf16_f32 v141, v144, v145
	flat_store_dwordx4 v[142:143], v[138:141]
	v_pk_fma_f32 v[170:171], v[136:137], v[112:113], v[164:165]
	v_pk_fma_f32 v[166:167], v[130:131], v[106:107], v[166:167]
	v_lshl_add_u64 v[138:139], v[218:219], 0, v[196:197]
	v_lshlrev_b64 v[134:135], 1, v[138:139]
	v_cvt_pk_bf16_f32 v130, v172, v173
	v_cvt_pk_bf16_f32 v131, v170, v171
	v_lshl_add_u64 v[136:137], s[12:13], 0, v[134:135]
	v_pk_fma_f32 v[168:169], v[132:133], v[108:109], v[168:169]
	v_cvt_pk_bf16_f32 v132, v166, v167
	v_lshl_add_u64 v[134:135], s[18:19], 0, v[134:135]
	v_cvt_pk_bf16_f32 v133, v168, v169
	v_lshlrev_b64 v[220:221], 11, v[198:199]
	v_pk_mul_f32 v[136:137], v[100:101], v[168:169]
	v_pk_mul_f32 v[130:131], v[102:103], v[172:173]
	v_pk_mul_f32 v[132:133], v[104:105], v[170:171]
	v_cvt_pk_bf16_f32 v130, v130, v131
	v_pk_mul_f32 v[138:139], v[98:99], v[166:167]
	v_cvt_pk_bf16_f32 v131, v132, v133
	v_pk_fma_f32 v[164:165], v[126:127], v[110:111], v[154:155]
	v_cvt_pk_bf16_f32 v132, v138, v139
	v_cvt_pk_bf16_f32 v133, v136, v137
	flat_store_dwordx4 v[134:135], v[130:133]
	v_pk_fma_f32 v[162:163], v[128:129], v[112:113], v[156:157]
	v_pk_fma_f32 v[158:159], v[122:123], v[106:107], v[158:159]
	v_lshl_add_u64 v[130:131], v[220:221], 0, v[196:197]
	v_lshlrev_b64 v[126:127], 1, v[130:131]
	v_cvt_pk_bf16_f32 v122, v164, v165
	v_cvt_pk_bf16_f32 v123, v162, v163
	v_lshl_add_u64 v[128:129], s[12:13], 0, v[126:127]
	v_pk_fma_f32 v[156:157], v[124:125], v[108:109], v[160:161]
	v_cvt_pk_bf16_f32 v124, v158, v159
	v_lshl_add_u64 v[126:127], s[18:19], 0, v[126:127]
	v_cvt_pk_bf16_f32 v125, v156, v157
	v_lshlrev_b64 v[222:223], 11, v[194:195]
	v_pk_mul_f32 v[128:129], v[100:101], v[156:157]
	v_pk_mul_f32 v[122:123], v[102:103], v[164:165]
	v_pk_mul_f32 v[124:125], v[104:105], v[162:163]
	v_cvt_pk_bf16_f32 v122, v122, v123
	v_pk_mul_f32 v[130:131], v[98:99], v[158:159]
	v_cvt_pk_bf16_f32 v123, v124, v125
	v_pk_fma_f32 v[154:155], v[118:119], v[110:111], v[146:147]
	v_cvt_pk_bf16_f32 v124, v130, v131
	v_cvt_pk_bf16_f32 v125, v128, v129
	flat_store_dwordx4 v[126:127], v[122:125]
	v_pk_fma_f32 v[146:147], v[116:117], v[108:109], v[152:153]
	v_add_u32_e32 v152, 0x80, v178
	v_lshl_add_u64 v[122:123], v[222:223], 0, v[196:197]
	v_lshlrev_b64 v[118:119], 1, v[122:123]
	v_pk_fma_f32 v[148:149], v[120:121], v[112:113], v[148:149]
	v_pk_fma_f32 v[150:151], v[114:115], v[106:107], v[150:151]
	v_cvt_pk_bf16_f32 v114, v154, v155
	v_cvt_pk_bf16_f32 v115, v148, v149
	v_lshl_add_u64 v[120:121], s[12:13], 0, v[118:119]
	v_cvt_pk_bf16_f32 v116, v150, v151
	v_cvt_pk_bf16_f32 v117, v146, v147
	v_ashrrev_i32_e32 v153, 31, v152
	v_lshl_add_u64 v[118:119], s[18:19], 0, v[118:119]
	s_and_b64 vcc, exec, s[8:9]
	v_pk_mul_f32 v[116:117], v[104:105], v[148:149]
	v_pk_mul_f32 v[114:115], v[102:103], v[154:155]
	v_lshlrev_b64 v[224:225], 13, v[152:153]
	v_add_u32_e32 v206, 0x90, v178
	v_add_u32_e32 v204, 0xa0, v178
	v_add_u32_e32 v202, 0xb0, v178
	v_pk_mul_f32 v[120:121], v[100:101], v[146:147]
	v_pk_mul_f32 v[122:123], v[98:99], v[150:151]
	v_cvt_pk_bf16_f32 v114, v114, v115
	v_cvt_pk_bf16_f32 v115, v116, v117
	s_nop 0
	v_cvt_pk_bf16_f32 v116, v122, v123
	v_cvt_pk_bf16_f32 v117, v120, v121
	flat_store_dwordx4 v[118:119], v[114:117]
	s_cbranch_vccnz .LBB0_1066
	s_nop 0
	v_lshl_add_u64 v[114:115], v[188:189], 0, v[224:225]
	v_ashrrev_i32_e32 v207, 31, v206
	global_load_dwordx4 v[142:145], v[114:115], off offset:16
	global_load_dwordx4 v[138:141], v[114:115], off
	v_lshlrev_b64 v[114:115], 13, v[206:207]
	v_lshl_add_u64 v[114:115], v[188:189], 0, v[114:115]
	v_ashrrev_i32_e32 v205, 31, v204
	global_load_dwordx4 v[134:137], v[114:115], off offset:16
	global_load_dwordx4 v[130:133], v[114:115], off
	v_lshlrev_b64 v[114:115], 13, v[204:205]
	v_lshl_add_u64 v[114:115], v[188:189], 0, v[114:115]
	v_ashrrev_i32_e32 v203, 31, v202
	global_load_dwordx4 v[126:129], v[114:115], off offset:16
	global_load_dwordx4 v[122:125], v[114:115], off
	v_lshlrev_b64 v[114:115], 13, v[202:203]
	v_lshl_add_u64 v[114:115], v[188:189], 0, v[114:115]
	global_load_dwordx4 v[118:121], v[114:115], off offset:16
	s_nop 0
	global_load_dwordx4 v[114:117], v[114:115], off
	v_lshlrev_b64 v[232:233], 12, v[152:153]
	s_cbranch_execnz .LBB0_1061

.LBB0_1061:
	v_lshlrev_b64 v[226:227], 11, v[152:153]
	v_lshl_add_u64 v[160:161], v[226:227], 0, v[196:197]
	s_waitcnt vmcnt(0)
	v_pk_fma_f32 v[152:153], v[94:95], v[110:111], v[138:139]
	v_lshlrev_b64 v[94:95], 1, v[160:161]
	v_pk_fma_f32 v[140:141], v[96:97], v[112:113], v[140:141]
	v_pk_fma_f32 v[138:139], v[92:93], v[108:109], v[144:145]
	v_pk_fma_f32 v[144:145], v[90:91], v[106:107], v[142:143]
	v_cvt_pk_bf16_f32 v90, v152, v153
	v_cvt_pk_bf16_f32 v91, v140, v141
	v_lshl_add_u64 v[96:97], s[12:13], 0, v[94:95]
	v_cvt_pk_bf16_f32 v92, v144, v145
	v_cvt_pk_bf16_f32 v93, v138, v139
	v_lshl_add_u64 v[94:95], s[18:19], 0, v[94:95]
	v_lshlrev_b64 v[228:229], 11, v[206:207]
	v_pk_mul_f32 v[90:91], v[102:103], v[152:153]
	v_pk_mul_f32 v[92:93], v[104:105], v[140:141]
	v_cvt_pk_bf16_f32 v90, v90, v91
	v_pk_mul_f32 v[96:97], v[100:101], v[138:139]
	v_cvt_pk_bf16_f32 v91, v92, v93
	v_pk_mul_f32 v[142:143], v[98:99], v[144:145]
	v_pk_fma_f32 v[160:161], v[86:87], v[110:111], v[130:131]
	v_cvt_pk_bf16_f32 v92, v142, v143
	v_cvt_pk_bf16_f32 v93, v96, v97
	flat_store_dwordx4 v[94:95], v[90:93]
	v_pk_fma_f32 v[142:143], v[88:89], v[112:113], v[132:133]
	v_pk_fma_f32 v[134:135], v[82:83], v[106:107], v[134:135]
	v_lshl_add_u64 v[90:91], v[228:229], 0, v[196:197]
	v_lshlrev_b64 v[86:87], 1, v[90:91]
	v_cvt_pk_bf16_f32 v82, v160, v161
	v_cvt_pk_bf16_f32 v83, v142, v143
	v_lshl_add_u64 v[88:89], s[12:13], 0, v[86:87]
	v_pk_fma_f32 v[136:137], v[84:85], v[108:109], v[136:137]
	v_cvt_pk_bf16_f32 v84, v134, v135
	v_lshl_add_u64 v[86:87], s[18:19], 0, v[86:87]
	v_cvt_pk_bf16_f32 v85, v136, v137
	v_lshlrev_b64 v[230:231], 11, v[204:205]
	v_pk_mul_f32 v[88:89], v[100:101], v[136:137]
	v_pk_mul_f32 v[82:83], v[102:103], v[160:161]
	v_pk_mul_f32 v[84:85], v[104:105], v[142:143]
	v_cvt_pk_bf16_f32 v82, v82, v83
	v_pk_mul_f32 v[90:91], v[98:99], v[134:135]
	v_cvt_pk_bf16_f32 v83, v84, v85
	v_pk_fma_f32 v[132:133], v[78:79], v[110:111], v[122:123]
	v_cvt_pk_bf16_f32 v84, v90, v91
	v_cvt_pk_bf16_f32 v85, v88, v89
	flat_store_dwordx4 v[86:87], v[82:85]
	v_pk_fma_f32 v[130:131], v[80:81], v[112:113], v[124:125]
	v_pk_fma_f32 v[126:127], v[74:75], v[106:107], v[126:127]
	v_lshl_add_u64 v[82:83], v[230:231], 0, v[196:197]
	v_lshlrev_b64 v[78:79], 1, v[82:83]
	v_cvt_pk_bf16_f32 v74, v132, v133
	v_cvt_pk_bf16_f32 v75, v130, v131
	v_lshl_add_u64 v[80:81], s[12:13], 0, v[78:79]
	v_pk_fma_f32 v[124:125], v[76:77], v[108:109], v[128:129]
	v_cvt_pk_bf16_f32 v76, v126, v127
	v_lshl_add_u64 v[78:79], s[18:19], 0, v[78:79]
	v_cvt_pk_bf16_f32 v77, v124, v125
	v_lshlrev_b64 v[128:129], 11, v[202:203]
	v_pk_mul_f32 v[80:81], v[100:101], v[124:125]
	v_pk_mul_f32 v[74:75], v[102:103], v[132:133]
	v_pk_mul_f32 v[76:77], v[104:105], v[130:131]
	v_cvt_pk_bf16_f32 v74, v74, v75
	v_pk_mul_f32 v[82:83], v[98:99], v[126:127]
	v_cvt_pk_bf16_f32 v75, v76, v77
	v_pk_fma_f32 v[122:123], v[70:71], v[110:111], v[114:115]
	v_cvt_pk_bf16_f32 v76, v82, v83
	v_cvt_pk_bf16_f32 v77, v80, v81
	flat_store_dwordx4 v[78:79], v[74:77]
	v_pk_fma_f32 v[116:117], v[72:73], v[112:113], v[116:117]
	v_pk_fma_f32 v[114:115], v[68:69], v[108:109], v[120:121]
	v_lshl_add_u64 v[74:75], v[128:129], 0, v[196:197]
	v_lshlrev_b64 v[70:71], 1, v[74:75]
	v_pk_fma_f32 v[118:119], v[66:67], v[106:107], v[118:119]
	v_cvt_pk_bf16_f32 v66, v122, v123
	v_cvt_pk_bf16_f32 v67, v116, v117
	v_lshl_add_u64 v[72:73], s[12:13], 0, v[70:71]
	v_cvt_pk_bf16_f32 v68, v118, v119
	v_cvt_pk_bf16_f32 v69, v114, v115
	v_lshl_add_u64 v[70:71], s[18:19], 0, v[70:71]
	v_pk_mul_f32 v[72:73], v[100:101], v[114:115]
	v_pk_mul_f32 v[68:69], v[104:105], v[116:117]
	v_pk_mul_f32 v[66:67], v[102:103], v[122:123]
	v_pk_mul_f32 v[74:75], v[98:99], v[118:119]
	v_cvt_pk_bf16_f32 v66, v66, v67
	v_cvt_pk_bf16_f32 v67, v68, v69
	s_and_b64 vcc, exec, s[8:9]
	v_cvt_pk_bf16_f32 v68, v74, v75
	v_cvt_pk_bf16_f32 v69, v72, v73
	flat_store_dwordx4 v[70:71], v[66:69]
	flat_load_dwordx4 v[78:81], v[208:209] offset:512
	flat_load_dwordx4 v[74:77], v[208:209] offset:528
	s_nop 0
	flat_load_dwordx4 v[70:73], v[210:211] offset:512
	flat_load_dwordx4 v[66:69], v[210:211] offset:528
	s_cbranch_vccnz .LBB0_1067
	v_lshl_add_u64 v[82:83], v[188:189], 0, v[212:213]
	global_load_dwordx4 v[110:113], v[82:83], off offset:528
	global_load_dwordx4 v[106:109], v[82:83], off offset:512
	v_lshlrev_b64 v[82:83], 13, v[200:201]
	v_lshl_add_u64 v[82:83], v[188:189], 0, v[82:83]
	global_load_dwordx4 v[102:105], v[82:83], off offset:528
	global_load_dwordx4 v[98:101], v[82:83], off offset:512
	v_lshlrev_b64 v[82:83], 13, v[198:199]
	v_lshl_add_u64 v[82:83], v[188:189], 0, v[82:83]
	global_load_dwordx4 v[94:97], v[82:83], off offset:528
	global_load_dwordx4 v[90:93], v[82:83], off offset:512
	v_lshlrev_b64 v[82:83], 13, v[194:195]
	v_lshl_add_u64 v[82:83], v[188:189], 0, v[82:83]
	global_load_dwordx4 v[86:89], v[82:83], off offset:528
	s_nop 0
	global_load_dwordx4 v[82:85], v[82:83], off offset:512
	s_mov_b64 s[30:31], 0
	s_branch .LBB0_1068

.LBB0_1070:
	v_lshl_add_u64 v[182:183], v[216:217], 0, v[120:121]
	s_waitcnt vmcnt(0) lgkmcnt(0)
	v_pk_fma_f32 v[198:199], v[62:63], v[78:79], v[106:107]
	v_lshlrev_b64 v[62:63], 1, v[182:183]
	v_pk_fma_f32 v[194:195], v[64:65], v[80:81], v[108:109]
	v_pk_fma_f32 v[110:111], v[58:59], v[74:75], v[110:111]
	v_cvt_pk_bf16_f32 v58, v198, v199
	v_cvt_pk_bf16_f32 v59, v194, v195
	v_lshl_add_u64 v[64:65], s[12:13], 0, v[62:63]
	v_pk_fma_f32 v[112:113], v[60:61], v[76:77], v[112:113]
	v_cvt_pk_bf16_f32 v60, v110, v111
	v_lshl_add_u64 v[62:63], s[18:19], 0, v[62:63]
	v_cvt_pk_bf16_f32 v61, v112, v113
	v_pk_mul_f32 v[64:65], v[68:69], v[112:113]
	v_pk_mul_f32 v[106:107], v[66:67], v[110:111]
	v_pk_mul_f32 v[58:59], v[70:71], v[198:199]
	v_pk_mul_f32 v[60:61], v[72:73], v[194:195]
	v_cvt_pk_bf16_f32 v58, v58, v59
	v_pk_fma_f32 v[108:109], v[54:55], v[78:79], v[98:99]
	v_cvt_pk_bf16_f32 v59, v60, v61
	v_cvt_pk_bf16_f32 v60, v106, v107
	v_cvt_pk_bf16_f32 v61, v64, v65
	flat_store_dwordx4 v[62:63], v[58:61]
	v_pk_fma_f32 v[106:107], v[56:57], v[80:81], v[100:101]
	v_pk_fma_f32 v[102:103], v[50:51], v[74:75], v[102:103]
	v_lshl_add_u64 v[58:59], v[218:219], 0, v[120:121]
	v_lshlrev_b64 v[54:55], 1, v[58:59]
	v_cvt_pk_bf16_f32 v50, v108, v109
	v_cvt_pk_bf16_f32 v51, v106, v107
	v_lshl_add_u64 v[56:57], s[12:13], 0, v[54:55]
	v_pk_fma_f32 v[104:105], v[52:53], v[76:77], v[104:105]
	v_cvt_pk_bf16_f32 v52, v102, v103
	v_lshl_add_u64 v[54:55], s[18:19], 0, v[54:55]
	v_cvt_pk_bf16_f32 v53, v104, v105
	v_pk_mul_f32 v[56:57], v[68:69], v[104:105]
	v_pk_mul_f32 v[58:59], v[66:67], v[102:103]
	v_pk_mul_f32 v[50:51], v[70:71], v[108:109]
	v_pk_mul_f32 v[52:53], v[72:73], v[106:107]
	v_cvt_pk_bf16_f32 v50, v50, v51
	v_pk_fma_f32 v[100:101], v[46:47], v[78:79], v[90:91]
	v_cvt_pk_bf16_f32 v51, v52, v53
	v_cvt_pk_bf16_f32 v52, v58, v59
	v_cvt_pk_bf16_f32 v53, v56, v57
	flat_store_dwordx4 v[54:55], v[50:53]
	v_pk_fma_f32 v[98:99], v[48:49], v[80:81], v[92:93]
	v_pk_fma_f32 v[94:95], v[42:43], v[74:75], v[94:95]
	v_lshl_add_u64 v[50:51], v[220:221], 0, v[120:121]
	v_lshlrev_b64 v[46:47], 1, v[50:51]
	v_cvt_pk_bf16_f32 v42, v100, v101
	v_cvt_pk_bf16_f32 v43, v98, v99
	v_lshl_add_u64 v[48:49], s[12:13], 0, v[46:47]
	v_pk_fma_f32 v[92:93], v[44:45], v[76:77], v[96:97]
	v_cvt_pk_bf16_f32 v44, v94, v95
	v_lshl_add_u64 v[46:47], s[18:19], 0, v[46:47]
	v_cvt_pk_bf16_f32 v45, v92, v93
	v_pk_mul_f32 v[48:49], v[68:69], v[92:93]
	v_pk_mul_f32 v[50:51], v[66:67], v[94:95]
	v_pk_mul_f32 v[42:43], v[70:71], v[100:101]
	v_pk_mul_f32 v[44:45], v[72:73], v[98:99]
	v_cvt_pk_bf16_f32 v42, v42, v43
	v_pk_fma_f32 v[90:91], v[38:39], v[78:79], v[82:83]
	v_cvt_pk_bf16_f32 v43, v44, v45
	v_cvt_pk_bf16_f32 v44, v50, v51
	v_cvt_pk_bf16_f32 v45, v48, v49
	flat_store_dwordx4 v[46:47], v[42:45]
	v_pk_fma_f32 v[84:85], v[40:41], v[80:81], v[84:85]
	v_pk_fma_f32 v[82:83], v[36:37], v[76:77], v[88:89]
	v_lshl_add_u64 v[42:43], v[222:223], 0, v[120:121]
	v_lshlrev_b64 v[38:39], 1, v[42:43]
	v_pk_fma_f32 v[86:87], v[34:35], v[74:75], v[86:87]
	v_cvt_pk_bf16_f32 v34, v90, v91
	v_cvt_pk_bf16_f32 v35, v84, v85
	v_lshl_add_u64 v[40:41], s[12:13], 0, v[38:39]
	v_cvt_pk_bf16_f32 v36, v86, v87
	v_cvt_pk_bf16_f32 v37, v82, v83
	v_lshl_add_u64 v[38:39], s[18:19], 0, v[38:39]
	s_and_b64 vcc, exec, s[8:9]
	v_pk_mul_f32 v[36:37], v[72:73], v[84:85]
	v_pk_mul_f32 v[34:35], v[70:71], v[90:91]
	v_pk_mul_f32 v[40:41], v[68:69], v[82:83]
	v_pk_mul_f32 v[42:43], v[66:67], v[86:87]
	v_cvt_pk_bf16_f32 v34, v34, v35
	v_cvt_pk_bf16_f32 v35, v36, v37
	s_nop 0
	v_cvt_pk_bf16_f32 v36, v42, v43
	v_cvt_pk_bf16_f32 v37, v40, v41
	flat_store_dwordx4 v[38:39], v[34:37]
	s_cbranch_vccnz .LBB0_1092
	s_nop 0
	v_lshl_add_u64 v[34:35], v[188:189], 0, v[224:225]
	global_load_dwordx4 v[62:65], v[34:35], off offset:528
	global_load_dwordx4 v[58:61], v[34:35], off offset:512
	v_lshlrev_b64 v[34:35], 13, v[206:207]
	v_lshl_add_u64 v[34:35], v[188:189], 0, v[34:35]
	global_load_dwordx4 v[54:57], v[34:35], off offset:528
	global_load_dwordx4 v[50:53], v[34:35], off offset:512
	v_lshlrev_b64 v[34:35], 13, v[204:205]
	v_lshl_add_u64 v[34:35], v[188:189], 0, v[34:35]
	global_load_dwordx4 v[46:49], v[34:35], off offset:528
	global_load_dwordx4 v[42:45], v[34:35], off offset:512
	v_lshlrev_b64 v[34:35], 13, v[202:203]
	v_lshl_add_u64 v[34:35], v[188:189], 0, v[34:35]
	global_load_dwordx4 v[38:41], v[34:35], off offset:528
	s_nop 0
	global_load_dwordx4 v[34:37], v[34:35], off offset:512
	s_cbranch_execnz .LBB0_1073

.LBB0_1073:
	v_mul_f32_e32 v88, v192, v192
	v_mul_f32_e32 v89, v190, v190
	v_fmac_f32_e32 v88, v193, v193
	v_fmac_f32_e32 v89, v191, v191
	v_add_f32_e32 v88, v89, v88
	v_mul_f32_e32 v89, v174, v174
	v_mul_f32_e32 v96, v177, v177
	v_fmac_f32_e32 v89, v175, v175
	v_fmac_f32_e32 v96, v176, v176
	v_add_f32_e32 v89, v96, v89
	v_add_f32_e32 v88, v89, v88
	v_mul_f32_e32 v89, v198, v198
	v_mul_f32_e32 v96, v194, v194
	v_fmac_f32_e32 v89, v199, v199
	v_fmac_f32_e32 v96, v195, v195
	v_add_f32_e32 v89, v96, v89
	v_mul_f32_e32 v96, v110, v110
	v_mul_f32_e32 v97, v113, v113
	v_fmac_f32_e32 v96, v111, v111
	v_fmac_f32_e32 v97, v112, v112
	v_add_f32_e32 v96, v97, v96
	v_add_f32_e32 v89, v96, v89
	v_add_f32_e32 v96, v88, v89
	v_lshl_add_u64 v[88:89], v[226:227], 0, v[120:121]
	s_waitcnt vmcnt(0)
	v_pk_fma_f32 v[26:27], v[26:27], v[74:75], v[62:63]
	v_lshlrev_b64 v[62:63], 1, v[88:89]
	v_pk_fma_f32 v[32:33], v[32:33], v[80:81], v[60:61]
	v_pk_fma_f32 v[30:31], v[30:31], v[78:79], v[58:59]
	v_pk_fma_f32 v[28:29], v[28:29], v[76:77], v[64:65]
	v_cvt_pk_bf16_f32 v58, v30, v31
	v_cvt_pk_bf16_f32 v59, v32, v33
	v_lshl_add_u64 v[64:65], s[12:13], 0, v[62:63]
	v_cvt_pk_bf16_f32 v60, v26, v27
	v_cvt_pk_bf16_f32 v61, v28, v29
	v_lshl_add_u64 v[62:63], s[18:19], 0, v[62:63]
	v_pk_mul_f32 v[64:65], v[68:69], v[28:29]
	v_pk_mul_f32 v[58:59], v[70:71], v[30:31]
	v_pk_mul_f32 v[60:61], v[72:73], v[32:33]
	v_cvt_pk_bf16_f32 v58, v58, v59
	v_pk_mul_f32 v[88:89], v[66:67], v[26:27]
	v_cvt_pk_bf16_f32 v59, v60, v61
	v_pk_fma_f32 v[18:19], v[18:19], v[74:75], v[54:55]
	v_cvt_pk_bf16_f32 v60, v88, v89
	v_cvt_pk_bf16_f32 v61, v64, v65
	flat_store_dwordx4 v[62:63], v[58:61]
	v_pk_fma_f32 v[24:25], v[24:25], v[80:81], v[52:53]
	v_pk_fma_f32 v[22:23], v[22:23], v[78:79], v[50:51]
	v_lshl_add_u64 v[58:59], v[228:229], 0, v[120:121]
	v_lshlrev_b64 v[54:55], 1, v[58:59]
	v_pk_fma_f32 v[20:21], v[20:21], v[76:77], v[56:57]
	v_cvt_pk_bf16_f32 v50, v22, v23
	v_cvt_pk_bf16_f32 v51, v24, v25
	v_lshl_add_u64 v[56:57], s[12:13], 0, v[54:55]
	v_cvt_pk_bf16_f32 v52, v18, v19
	v_cvt_pk_bf16_f32 v53, v20, v21
	v_lshl_add_u64 v[54:55], s[18:19], 0, v[54:55]
	v_pk_mul_f32 v[56:57], v[68:69], v[20:21]
	v_pk_mul_f32 v[50:51], v[70:71], v[22:23]
	v_pk_mul_f32 v[52:53], v[72:73], v[24:25]
	v_cvt_pk_bf16_f32 v50, v50, v51
	v_pk_mul_f32 v[58:59], v[66:67], v[18:19]
	v_cvt_pk_bf16_f32 v51, v52, v53
	v_pk_fma_f32 v[10:11], v[10:11], v[74:75], v[46:47]
	v_cvt_pk_bf16_f32 v52, v58, v59
	v_cvt_pk_bf16_f32 v53, v56, v57
	flat_store_dwordx4 v[54:55], v[50:53]
	v_pk_fma_f32 v[16:17], v[16:17], v[80:81], v[44:45]
	v_pk_fma_f32 v[14:15], v[14:15], v[78:79], v[42:43]
	v_lshl_add_u64 v[50:51], v[230:231], 0, v[120:121]
	v_lshlrev_b64 v[46:47], 1, v[50:51]
	v_pk_fma_f32 v[12:13], v[12:13], v[76:77], v[48:49]
	v_cvt_pk_bf16_f32 v42, v14, v15
	v_cvt_pk_bf16_f32 v43, v16, v17
	v_lshl_add_u64 v[48:49], s[12:13], 0, v[46:47]
	v_cvt_pk_bf16_f32 v44, v10, v11
	v_cvt_pk_bf16_f32 v45, v12, v13
	v_lshl_add_u64 v[46:47], s[18:19], 0, v[46:47]
	v_pk_mul_f32 v[48:49], v[68:69], v[12:13]
	v_pk_mul_f32 v[42:43], v[70:71], v[14:15]
	v_pk_mul_f32 v[44:45], v[72:73], v[16:17]
	v_cvt_pk_bf16_f32 v42, v42, v43
	v_pk_mul_f32 v[50:51], v[66:67], v[10:11]
	v_cvt_pk_bf16_f32 v43, v44, v45
	v_pk_fma_f32 v[2:3], v[2:3], v[74:75], v[38:39]
	v_cvt_pk_bf16_f32 v44, v50, v51
	v_cvt_pk_bf16_f32 v45, v48, v49
	flat_store_dwordx4 v[46:47], v[42:45]
	v_pk_fma_f32 v[8:9], v[8:9], v[80:81], v[36:37]
	v_pk_fma_f32 v[6:7], v[6:7], v[78:79], v[34:35]
	v_lshl_add_u64 v[42:43], v[128:129], 0, v[120:121]
	v_lshlrev_b64 v[38:39], 1, v[42:43]
	v_pk_fma_f32 v[4:5], v[4:5], v[76:77], v[40:41]
	v_cvt_pk_bf16_f32 v34, v6, v7
	v_cvt_pk_bf16_f32 v35, v8, v9
	v_cvt_pk_bf16_f32 v36, v2, v3
	v_lshl_add_u64 v[40:41], s[12:13], 0, v[38:39]
	v_cvt_pk_bf16_f32 v37, v4, v5
	v_pk_mul_f32 v[42:43], v[66:67], v[2:3]
	v_lshl_add_u64 v[38:39], s[18:19], 0, v[38:39]
	v_pk_mul_f32 v[36:37], v[72:73], v[8:9]
	v_pk_mul_f32 v[34:35], v[70:71], v[6:7]
	v_pk_mul_f32 v[40:41], v[68:69], v[4:5]
	v_cvt_pk_bf16_f32 v34, v34, v35
	v_cvt_pk_bf16_f32 v35, v36, v37
	v_cvt_pk_bf16_f32 v36, v42, v43
	ds_swizzle_b32 v42, v96 offset:swizzle(SWAP,16)
	v_cvt_pk_bf16_f32 v37, v40, v41
	flat_store_dwordx4 v[38:39], v[34:37]
	v_cmp_eq_u32_e32 vcc, 0, v245
	s_waitcnt lgkmcnt(0)
	v_add_f32_e32 v36, v96, v42
	v_mov_b32_e32 v37, v36
	s_nop 1
	v_permlane32_swap_b32_e32 v36, v37
	v_lshl_add_u64 v[34:35], v[178:179], 3, s[20:21]
	s_and_saveexec_b64 s[30:31], vcc
	s_cbranch_execz .LBB0_1075
	v_add_f32_e32 v36, v36, v37
	v_mul_f32_e32 v36, 0x49800000, v36
	v_trunc_f32_e32 v36, v36
	v_mul_f32_e64 v37, |v36|, s78
	v_floor_f32_e32 v37, v37
	v_fma_f32 v38, v37, s74, |v36|
	v_cvt_u32_f32_e32 v38, v38
	v_cvt_u32_f32_e32 v37, v37
	v_ashrrev_i32_e32 v39, 31, v36
	v_xor_b32_e32 v36, v38, v39
	v_xor_b32_e32 v37, v37, v39
	v_sub_co_u32_e64 v36, s[8:9], v36, v39
	s_nop 1
	v_subb_co_u32_e64 v37, s[8:9], v37, v39, s[8:9]
	global_atomic_add_x2 v[34:35], v[36:37], off

.LBB0_1236:
	v_mbcnt_lo_u32_b32 v156, -1, 0
	v_mbcnt_hi_u32_b32 v156, -1, v156
	s_lshl_b32 s0, s0, 8
	v_bfe_u32 v229, v156, 4, 2
	v_lshl_or_b32 v90, v229, 3, s0
	s_lshl_b32 s0, s1, 7
	v_or_b32_e32 v176, s82, v90
	s_and_b32 s0, s0, 0xfffff800
	v_add_u32_e32 v154, s0, v176
	v_ashrrev_i32_e32 v155, 31, v154
	v_lshl_add_u64 v[178:179], v[154:155], 2, s[14:15]
	flat_load_dwordx4 v[110:113], v[178:179]
	flat_load_dwordx4 v[106:109], v[178:179] offset:16
	s_mov_b32 s96, 0xfffb8000
	s_mov_b32 s97, -1
	s_mov_b32 s98, 0xe2e00000
	s_mov_b32 s99, -1
	v_lshl_add_u64 v[244:245], v[178:179], 0, s[96:97]
	global_load_dwordx4 v[232:235], v[244:245], off
	global_load_dwordx4 v[240:243], v[244:245], off offset:16
	v_mov_b32_e32 v90, 0
	s_and_b64 vcc, exec, s[10:11]
	v_mov_b32_e32 v98, 0
	v_mov_b32_e32 v99, 0
	v_mov_b32_e32 v100, 0
	v_mov_b32_e32 v101, 0
	v_mov_b32_e32 v94, 0
	v_mov_b32_e32 v95, 0
	v_mov_b32_e32 v96, 0
	v_mov_b32_e32 v97, 0
	s_cbranch_vccz .LBB0_1238
	v_lshl_add_u64 v[92:93], v[154:155], 2, s[16:17]
	flat_load_dwordx4 v[98:101], v[92:93]
	flat_load_dwordx4 v[94:97], v[92:93] offset:16

.LBB0_1240:
	s_lshl_b32 s1, s1, 8
	s_add_i32 s1, s1, s72
	v_and_or_b32 v166, v156, 15, s1
	v_ashrrev_i32_e32 v177, 31, v176
	v_ashrrev_i32_e32 v167, 31, v166
	v_lshl_add_u64 v[170:171], v[176:177], 1, s[12:13]
	v_lshlrev_b64 v[188:189], 12, v[166:167]
	v_lshl_add_u64 v[186:187], v[170:171], 0, v[188:189]
	v_or_b32_e32 v198, 16, v166
	v_or_b32_e32 v200, 32, v166
	v_or_b32_e32 v174, 48, v166
	v_lshl_add_u64 v[246:247], v[186:187], 0, s[98:99]
	flat_load_dwordx4 v[182:185], v[246:247]
	v_ashrrev_i32_e32 v199, 31, v198
	v_ashrrev_i32_e32 v201, 31, v200
	v_ashrrev_i32_e32 v175, 31, v174
	v_lshlrev_b64 v[190:191], 12, v[198:199]
	v_lshlrev_b64 v[192:193], 12, v[200:201]
	v_lshlrev_b64 v[194:195], 12, v[174:175]
	v_lshl_add_u64 v[204:205], v[170:171], 0, v[190:191]
	v_lshl_add_u64 v[202:203], v[170:171], 0, v[192:193]
	v_lshl_add_u64 v[172:173], v[170:171], 0, v[194:195]
	v_lshl_add_u64 v[246:247], v[204:205], 0, s[98:99]
	flat_load_dwordx4 v[162:165], v[246:247]
	v_lshl_add_u64 v[246:247], v[202:203], 0, s[98:99]
	flat_load_dwordx4 v[158:161], v[246:247]
	v_lshl_add_u64 v[246:247], v[172:173], 0, s[98:99]
	flat_load_dwordx4 v[154:157], v[246:247]
	v_lshlrev_b64 v[196:197], 11, v[166:167]
	v_lshl_add_u64 v[206:207], v[196:197], 0, v[176:177]
	s_andn2_b64 vcc, exec, s[10:11]
	s_waitcnt vmcnt(0) lgkmcnt(0)
	v_rcp_f32_e32 v232, v232
	v_rcp_f32_e32 v233, v233
	v_rcp_f32_e32 v234, v234
	v_rcp_f32_e32 v235, v235
	v_rcp_f32_e32 v240, v240
	v_rcp_f32_e32 v241, v241
	v_rcp_f32_e32 v242, v242
	v_rcp_f32_e32 v243, v243
	s_nop 0
	v_lshlrev_b32_e32 v168, 16, v182
	v_and_b32_e32 v169, 0xffff0000, v182
	v_lshlrev_b32_e32 v208, 16, v184
	v_and_b32_e32 v209, 0xffff0000, v184
	v_lshlrev_b32_e32 v184, 16, v185
	v_and_b32_e32 v185, 0xffff0000, v185
	v_lshlrev_b32_e32 v182, 16, v183
	v_and_b32_e32 v183, 0xffff0000, v183
	v_pk_mul_f32 v[168:169], v[168:169], v[232:233]
	v_pk_fma_f32 v[168:169], v[150:151], v[110:111], v[168:169]
	v_pk_mul_f32 v[208:209], v[208:209], v[240:241]
	v_pk_fma_f32 v[150:151], v[146:147], v[106:107], v[208:209]
	v_pk_mul_f32 v[184:185], v[184:185], v[242:243]
	v_pk_fma_f32 v[146:147], v[148:149], v[108:109], v[184:185]
	v_cndmask_b32_e64 v148, 0, 1, s[10:11]
	v_pk_mul_f32 v[182:183], v[182:183], v[234:235]
	v_pk_fma_f32 v[152:153], v[152:153], v[112:113], v[182:183]
	v_cmp_ne_u32_e64 s[8:9], 1, v148
	v_cvt_pk_bf16_f32 v182, v168, v169
	v_cvt_pk_bf16_f32 v183, v152, v153
	v_cvt_pk_bf16_f32 v184, v150, v151
	v_cvt_pk_bf16_f32 v185, v146, v147
	flat_store_dwordx4 v[186:187], v[182:185]
	s_cbranch_vccnz .LBB0_1242
	v_pk_mul_f32 v[148:149], v[100:101], v[152:153]
	v_pk_mul_f32 v[182:183], v[98:99], v[168:169]
	v_pk_mul_f32 v[184:185], v[94:95], v[150:151]
	v_cvt_pk_bf16_f32 v182, v182, v183
	v_cvt_pk_bf16_f32 v183, v148, v149
	v_lshl_add_u64 v[148:149], v[206:207], 1, s[18:19]
	v_pk_mul_f32 v[186:187], v[96:97], v[146:147]
	v_cvt_pk_bf16_f32 v184, v184, v185
	s_nop 0
	v_cvt_pk_bf16_f32 v185, v186, v187
	flat_store_dwordx4 v[148:149], v[182:185]

.LBB0_1244:
	s_nop 1
	v_lshlrev_b32_e32 v182, 16, v162
	v_and_b32_e32 v183, 0xffff0000, v162
	v_lshlrev_b32_e32 v162, 16, v163
	v_and_b32_e32 v163, 0xffff0000, v163
	v_lshlrev_b32_e32 v184, 16, v164
	v_and_b32_e32 v185, 0xffff0000, v164
	v_lshlrev_b32_e32 v164, 16, v165
	v_and_b32_e32 v165, 0xffff0000, v165
	v_lshlrev_b64 v[198:199], 11, v[198:199]
	v_lshl_add_u64 v[148:149], v[198:199], 0, v[176:177]
	v_pk_mul_f32 v[162:163], v[162:163], v[234:235]
	v_pk_fma_f32 v[144:145], v[144:145], v[112:113], v[162:163]
	v_pk_mul_f32 v[182:183], v[182:183], v[232:233]
	v_pk_fma_f32 v[142:143], v[142:143], v[110:111], v[182:183]
	v_pk_mul_f32 v[184:185], v[184:185], v[240:241]
	v_pk_fma_f32 v[138:139], v[138:139], v[106:107], v[184:185]
	v_pk_mul_f32 v[164:165], v[164:165], v[242:243]
	v_pk_fma_f32 v[140:141], v[140:141], v[108:109], v[164:165]
	s_and_b64 vcc, exec, s[8:9]
	v_cvt_pk_bf16_f32 v162, v142, v143
	v_cvt_pk_bf16_f32 v163, v144, v145
	v_cvt_pk_bf16_f32 v164, v138, v139
	v_cvt_pk_bf16_f32 v165, v140, v141
	flat_store_dwordx4 v[204:205], v[162:165]
	s_cbranch_vccnz .LBB0_1246
	s_nop 0
	v_pk_mul_f32 v[164:165], v[100:101], v[144:145]
	v_pk_mul_f32 v[162:163], v[98:99], v[142:143]
	v_pk_mul_f32 v[182:183], v[96:97], v[140:141]
	v_pk_mul_f32 v[184:185], v[94:95], v[138:139]
	v_cvt_pk_bf16_f32 v162, v162, v163
	v_cvt_pk_bf16_f32 v163, v164, v165
	s_nop 0
	v_cvt_pk_bf16_f32 v164, v184, v185
	v_cvt_pk_bf16_f32 v165, v182, v183
	v_lshl_add_u64 v[182:183], v[148:149], 1, s[18:19]
	flat_store_dwordx4 v[182:183], v[162:165]

.LBB0_1248:
	v_lshlrev_b32_e32 v148, 16, v158
	v_and_b32_e32 v149, 0xffff0000, v158
	v_lshlrev_b32_e32 v158, 16, v159
	v_and_b32_e32 v159, 0xffff0000, v159
	v_lshlrev_b32_e32 v162, 16, v160
	v_and_b32_e32 v163, 0xffff0000, v160
	v_lshlrev_b32_e32 v164, 16, v161
	v_and_b32_e32 v165, 0xffff0000, v161
	v_lshlrev_b64 v[200:201], 11, v[200:201]
	v_lshl_add_u64 v[160:161], v[200:201], 0, v[176:177]
	v_pk_mul_f32 v[158:159], v[158:159], v[234:235]
	v_pk_fma_f32 v[136:137], v[136:137], v[112:113], v[158:159]
	v_pk_mul_f32 v[148:149], v[148:149], v[232:233]
	v_pk_fma_f32 v[134:135], v[134:135], v[110:111], v[148:149]
	v_pk_mul_f32 v[162:163], v[162:163], v[240:241]
	v_pk_fma_f32 v[148:149], v[130:131], v[106:107], v[162:163]
	v_pk_mul_f32 v[164:165], v[164:165], v[242:243]
	v_pk_fma_f32 v[158:159], v[132:133], v[108:109], v[164:165]
	s_and_b64 vcc, exec, s[8:9]
	v_cvt_pk_bf16_f32 v130, v134, v135
	v_cvt_pk_bf16_f32 v131, v136, v137
	v_cvt_pk_bf16_f32 v132, v148, v149
	v_cvt_pk_bf16_f32 v133, v158, v159
	flat_store_dwordx4 v[202:203], v[130:133]
	s_cbranch_vccnz .LBB0_1250
	s_nop 0
	v_pk_mul_f32 v[132:133], v[100:101], v[136:137]
	v_pk_mul_f32 v[130:131], v[98:99], v[134:135]
	v_pk_mul_f32 v[162:163], v[96:97], v[158:159]
	v_pk_mul_f32 v[164:165], v[94:95], v[148:149]
	v_cvt_pk_bf16_f32 v130, v130, v131
	v_cvt_pk_bf16_f32 v131, v132, v133
	s_nop 0
	v_cvt_pk_bf16_f32 v132, v164, v165
	v_cvt_pk_bf16_f32 v133, v162, v163
	v_lshl_add_u64 v[162:163], v[160:161], 1, s[18:19]
	flat_store_dwordx4 v[162:163], v[130:133]

.LBB0_1252:
	s_nop 1
	v_lshlrev_b32_e32 v132, 16, v154
	v_and_b32_e32 v133, 0xffff0000, v154
	v_lshlrev_b32_e32 v154, 16, v155
	v_and_b32_e32 v155, 0xffff0000, v155
	v_lshlrev_b32_e32 v160, 16, v156
	v_and_b32_e32 v161, 0xffff0000, v156
	v_lshlrev_b32_e32 v162, 16, v157
	v_and_b32_e32 v163, 0xffff0000, v157
	v_lshlrev_b64 v[202:203], 11, v[174:175]
	v_lshl_add_u64 v[130:131], v[202:203], 0, v[176:177]
	v_pk_mul_f32 v[154:155], v[154:155], v[234:235]
	v_pk_fma_f32 v[154:155], v[128:129], v[112:113], v[154:155]
	v_pk_mul_f32 v[132:133], v[132:133], v[232:233]
	v_pk_fma_f32 v[156:157], v[126:127], v[110:111], v[132:133]
	v_pk_mul_f32 v[160:161], v[160:161], v[240:241]
	v_pk_fma_f32 v[160:161], v[122:123], v[106:107], v[160:161]
	v_pk_mul_f32 v[162:163], v[162:163], v[242:243]
	v_pk_fma_f32 v[162:163], v[124:125], v[108:109], v[162:163]
	s_and_b64 vcc, exec, s[8:9]
	v_cvt_pk_bf16_f32 v122, v156, v157
	v_cvt_pk_bf16_f32 v123, v154, v155
	v_cvt_pk_bf16_f32 v124, v160, v161
	v_cvt_pk_bf16_f32 v125, v162, v163
	flat_store_dwordx4 v[172:173], v[122:125]
	s_cbranch_vccnz .LBB0_1254
	s_nop 0
	v_pk_mul_f32 v[124:125], v[100:101], v[154:155]
	v_pk_mul_f32 v[122:123], v[98:99], v[156:157]
	v_pk_mul_f32 v[126:127], v[96:97], v[162:163]
	v_pk_mul_f32 v[128:129], v[94:95], v[160:161]
	v_cvt_pk_bf16_f32 v122, v122, v123
	v_cvt_pk_bf16_f32 v123, v124, v125
	s_nop 0
	v_cvt_pk_bf16_f32 v124, v128, v129
	v_cvt_pk_bf16_f32 v125, v126, v127
	v_lshl_add_u64 v[126:127], v[130:131], 1, s[18:19]
	flat_store_dwordx4 v[126:127], v[122:125]

.LBB0_1256:
	v_add_u32_e32 v186, 0x80, v166
	v_ashrrev_i32_e32 v187, 31, v186
	v_lshlrev_b64 v[204:205], 12, v[186:187]
	v_add_u32_e32 v164, 0x90, v166
	v_add_u32_e32 v172, 0xa0, v166
	v_add_u32_e32 v220, 0xb0, v166
	v_lshl_add_u64 v[214:215], v[170:171], 0, v[204:205]
	v_ashrrev_i32_e32 v165, 31, v164
	v_ashrrev_i32_e32 v173, 31, v172
	v_ashrrev_i32_e32 v221, 31, v220
	v_lshl_add_u64 v[246:247], v[214:215], 0, s[98:99]
	flat_load_dwordx4 v[182:185], v[246:247]
	v_lshlrev_b64 v[206:207], 12, v[164:165]
	v_lshlrev_b64 v[208:209], 12, v[172:173]
	v_lshlrev_b64 v[210:211], 12, v[220:221]
	v_lshl_add_u64 v[174:175], v[170:171], 0, v[206:207]
	v_lshl_add_u64 v[222:223], v[170:171], 0, v[208:209]
	v_lshl_add_u64 v[218:219], v[170:171], 0, v[210:211]
	v_lshl_add_u64 v[246:247], v[174:175], 0, s[98:99]
	flat_load_dwordx4 v[130:133], v[246:247]
	v_lshl_add_u64 v[246:247], v[222:223], 0, s[98:99]
	flat_load_dwordx4 v[126:129], v[246:247]
	v_lshl_add_u64 v[246:247], v[218:219], 0, s[98:99]
	flat_load_dwordx4 v[122:125], v[246:247]
	v_lshlrev_b64 v[212:213], 11, v[186:187]
	v_lshl_add_u64 v[170:171], v[212:213], 0, v[176:177]
	s_and_b64 vcc, exec, s[8:9]
	s_waitcnt vmcnt(0) lgkmcnt(0)
	v_lshlrev_b32_e32 v216, 16, v182
	v_and_b32_e32 v217, 0xffff0000, v182
	v_lshlrev_b32_e32 v182, 16, v183
	v_and_b32_e32 v183, 0xffff0000, v183
	v_lshlrev_b32_e32 v230, 16, v184
	v_and_b32_e32 v231, 0xffff0000, v184
	v_lshlrev_b32_e32 v184, 16, v185
	v_and_b32_e32 v185, 0xffff0000, v185
	v_pk_mul_f32 v[182:183], v[182:183], v[234:235]
	v_pk_fma_f32 v[120:121], v[120:121], v[112:113], v[182:183]
	v_pk_mul_f32 v[216:217], v[216:217], v[232:233]
	v_pk_fma_f32 v[118:119], v[118:119], v[110:111], v[216:217]
	v_pk_mul_f32 v[230:231], v[230:231], v[240:241]
	v_pk_fma_f32 v[114:115], v[114:115], v[106:107], v[230:231]
	v_pk_mul_f32 v[184:185], v[184:185], v[242:243]
	v_pk_fma_f32 v[116:117], v[116:117], v[108:109], v[184:185]
	v_cvt_pk_bf16_f32 v182, v118, v119
	v_cvt_pk_bf16_f32 v183, v120, v121
	v_cvt_pk_bf16_f32 v184, v114, v115
	s_nop 0
	v_cvt_pk_bf16_f32 v185, v116, v117
	flat_store_dwordx4 v[214:215], v[182:185]
	s_cbranch_vccnz .LBB0_1258
	s_nop 0
	v_pk_mul_f32 v[184:185], v[100:101], v[120:121]
	v_pk_mul_f32 v[182:183], v[98:99], v[118:119]
	v_pk_mul_f32 v[186:187], v[96:97], v[116:117]
	v_pk_mul_f32 v[214:215], v[94:95], v[114:115]
	v_cvt_pk_bf16_f32 v182, v182, v183
	v_cvt_pk_bf16_f32 v183, v184, v185
	s_nop 0
	v_cvt_pk_bf16_f32 v184, v214, v215
	v_cvt_pk_bf16_f32 v185, v186, v187
	v_lshl_add_u64 v[186:187], v[170:171], 1, s[18:19]
	flat_store_dwordx4 v[186:187], v[182:185]

.LBB0_1260:
	v_lshlrev_b32_e32 v170, 16, v130
	v_and_b32_e32 v171, 0xffff0000, v130
	v_lshlrev_b32_e32 v130, 16, v131
	v_and_b32_e32 v131, 0xffff0000, v131
	v_lshlrev_b32_e32 v182, 16, v132
	v_and_b32_e32 v183, 0xffff0000, v132
	v_lshlrev_b32_e32 v184, 16, v133
	v_and_b32_e32 v185, 0xffff0000, v133
	v_lshlrev_b64 v[214:215], 11, v[164:165]
	v_lshl_add_u64 v[216:217], v[214:215], 0, v[176:177]
	v_pk_mul_f32 v[130:131], v[130:131], v[234:235]
	v_pk_fma_f32 v[130:131], v[88:89], v[112:113], v[130:131]
	v_pk_mul_f32 v[170:171], v[170:171], v[232:233]
	v_pk_fma_f32 v[132:133], v[86:87], v[110:111], v[170:171]
	v_pk_mul_f32 v[182:183], v[182:183], v[240:241]
	v_pk_fma_f32 v[164:165], v[82:83], v[106:107], v[182:183]
	v_pk_mul_f32 v[184:185], v[184:185], v[242:243]
	v_pk_fma_f32 v[170:171], v[84:85], v[108:109], v[184:185]
	s_and_b64 vcc, exec, s[8:9]
	v_cvt_pk_bf16_f32 v82, v132, v133
	v_cvt_pk_bf16_f32 v83, v130, v131
	v_cvt_pk_bf16_f32 v84, v164, v165
	v_cvt_pk_bf16_f32 v85, v170, v171
	flat_store_dwordx4 v[174:175], v[82:85]
	s_cbranch_vccnz .LBB0_1262
	s_nop 0
	v_pk_mul_f32 v[84:85], v[100:101], v[130:131]
	v_pk_mul_f32 v[82:83], v[98:99], v[132:133]
	v_pk_mul_f32 v[86:87], v[96:97], v[170:171]
	v_pk_mul_f32 v[88:89], v[94:95], v[164:165]
	v_cvt_pk_bf16_f32 v82, v82, v83
	v_cvt_pk_bf16_f32 v83, v84, v85
	s_nop 0
	v_cvt_pk_bf16_f32 v84, v88, v89
	v_cvt_pk_bf16_f32 v85, v86, v87
	v_lshl_add_u64 v[86:87], v[216:217], 1, s[18:19]
	flat_store_dwordx4 v[86:87], v[82:85]

.LBB0_1264:
	s_nop 1
	v_lshlrev_b32_e32 v84, 16, v126
	v_and_b32_e32 v85, 0xffff0000, v126
	v_lshlrev_b32_e32 v86, 16, v127
	v_and_b32_e32 v87, 0xffff0000, v127
	v_lshlrev_b32_e32 v88, 16, v128
	v_and_b32_e32 v89, 0xffff0000, v128
	v_lshlrev_b32_e32 v174, 16, v129
	v_and_b32_e32 v175, 0xffff0000, v129
	v_lshlrev_b64 v[216:217], 11, v[172:173]
	v_lshl_add_u64 v[82:83], v[216:217], 0, v[176:177]
	v_pk_mul_f32 v[86:87], v[86:87], v[234:235]
	v_pk_fma_f32 v[126:127], v[80:81], v[112:113], v[86:87]
	v_pk_mul_f32 v[84:85], v[84:85], v[232:233]
	v_pk_fma_f32 v[128:129], v[78:79], v[110:111], v[84:85]
	v_pk_mul_f32 v[88:89], v[88:89], v[240:241]
	v_pk_fma_f32 v[172:173], v[74:75], v[106:107], v[88:89]
	v_pk_mul_f32 v[174:175], v[174:175], v[242:243]
	v_pk_fma_f32 v[174:175], v[76:77], v[108:109], v[174:175]
	s_and_b64 vcc, exec, s[8:9]
	v_cvt_pk_bf16_f32 v74, v128, v129
	v_cvt_pk_bf16_f32 v75, v126, v127
	v_cvt_pk_bf16_f32 v76, v172, v173
	v_cvt_pk_bf16_f32 v77, v174, v175
	flat_store_dwordx4 v[222:223], v[74:77]
	s_cbranch_vccnz .LBB0_1266
	s_nop 0
	v_pk_mul_f32 v[76:77], v[100:101], v[126:127]
	v_pk_mul_f32 v[74:75], v[98:99], v[128:129]
	v_pk_mul_f32 v[78:79], v[96:97], v[174:175]
	v_pk_mul_f32 v[80:81], v[94:95], v[172:173]
	v_cvt_pk_bf16_f32 v74, v74, v75
	v_cvt_pk_bf16_f32 v75, v76, v77
	s_nop 0
	v_cvt_pk_bf16_f32 v76, v80, v81
	v_cvt_pk_bf16_f32 v77, v78, v79
	v_lshl_add_u64 v[78:79], v[82:83], 1, s[18:19]
	flat_store_dwordx4 v[78:79], v[74:77]

.LBB0_1268:
	s_nop 1
	v_lshlrev_b32_e32 v76, 16, v122
	v_and_b32_e32 v77, 0xffff0000, v122
	v_lshlrev_b32_e32 v78, 16, v123
	v_and_b32_e32 v79, 0xffff0000, v123
	v_lshlrev_b32_e32 v80, 16, v124
	v_and_b32_e32 v81, 0xffff0000, v124
	v_lshlrev_b32_e32 v82, 16, v125
	v_and_b32_e32 v83, 0xffff0000, v125
	v_lshlrev_b64 v[122:123], 11, v[220:221]
	v_lshl_add_u64 v[74:75], v[122:123], 0, v[176:177]
	v_pk_mul_f32 v[78:79], v[78:79], v[234:235]
	v_pk_fma_f32 v[112:113], v[72:73], v[112:113], v[78:79]
	v_pk_mul_f32 v[76:77], v[76:77], v[232:233]
	v_pk_fma_f32 v[110:111], v[70:71], v[110:111], v[76:77]
	v_pk_mul_f32 v[80:81], v[80:81], v[240:241]
	v_pk_fma_f32 v[106:107], v[66:67], v[106:107], v[80:81]
	v_pk_mul_f32 v[82:83], v[82:83], v[242:243]
	v_pk_fma_f32 v[108:109], v[68:69], v[108:109], v[82:83]
	s_and_b64 vcc, exec, s[8:9]
	v_cvt_pk_bf16_f32 v66, v110, v111
	v_cvt_pk_bf16_f32 v67, v112, v113
	v_cvt_pk_bf16_f32 v68, v106, v107
	v_cvt_pk_bf16_f32 v69, v108, v109
	flat_store_dwordx4 v[218:219], v[66:69]
	s_cbranch_vccnz .LBB0_1270
	s_nop 0
	v_pk_mul_f32 v[68:69], v[100:101], v[112:113]
	v_pk_mul_f32 v[66:67], v[98:99], v[110:111]
	v_pk_mul_f32 v[70:71], v[96:97], v[108:109]
	v_pk_mul_f32 v[72:73], v[94:95], v[106:107]
	v_cvt_pk_bf16_f32 v66, v66, v67
	v_cvt_pk_bf16_f32 v67, v68, v69
	s_nop 0
	v_cvt_pk_bf16_f32 v68, v72, v73
	v_cvt_pk_bf16_f32 v69, v70, v71
	v_lshl_add_u64 v[70:71], v[74:75], 1, s[18:19]
	flat_store_dwordx4 v[70:71], v[66:69]

.LBB0_1272:
	flat_load_dwordx4 v[86:89], v[178:179] offset:512
	flat_load_dwordx4 v[82:85], v[178:179] offset:528
	v_lshl_add_u64 v[244:245], v[178:179], 0, s[96:97]
	global_load_dwordx4 v[232:235], v[244:245], off offset:512
	global_load_dwordx4 v[240:243], v[244:245], off offset:528
	v_or_b32_e32 v102, 0x80, v176
	v_add_u32_e32 v90, s0, v102
	v_ashrrev_i32_e32 v91, 31, v90
	v_mov_b32_e32 v66, 0
	s_and_b64 vcc, exec, s[8:9]
	v_mov_b32_e32 v74, 0
	v_mov_b32_e32 v75, 0
	v_mov_b32_e32 v76, 0
	v_mov_b32_e32 v77, 0
	v_mov_b32_e32 v70, 0
	v_mov_b32_e32 v71, 0
	v_mov_b32_e32 v72, 0
	v_mov_b32_e32 v73, 0
	s_cbranch_vccnz .LBB0_1274
	v_lshl_add_u64 v[68:69], v[90:91], 2, s[16:17]
	flat_load_dwordx4 v[74:77], v[68:69]
	flat_load_dwordx4 v[70:73], v[68:69] offset:16

.LBB0_1276:
	v_ashrrev_i32_e32 v103, 31, v102
	v_lshl_add_u64 v[90:91], s[12:13], 0, v[188:189]
	v_lshlrev_b64 v[104:105], 1, v[102:103]
	v_lshl_add_u64 v[186:187], v[90:91], 0, v[104:105]
	v_lshl_add_u64 v[90:91], s[12:13], 0, v[190:191]
	v_lshl_add_u64 v[246:247], v[186:187], 0, s[98:99]
	flat_load_dwordx4 v[182:185], v[246:247]
	v_lshl_add_u64 v[92:93], s[12:13], 0, v[192:193]
	v_lshl_add_u64 v[94:95], s[12:13], 0, v[194:195]
	v_lshl_add_u64 v[178:179], v[90:91], 0, v[104:105]
	v_lshl_add_u64 v[176:177], v[92:93], 0, v[104:105]
	v_lshl_add_u64 v[124:125], v[94:95], 0, v[104:105]
	v_lshl_add_u64 v[246:247], v[178:179], 0, s[98:99]
	flat_load_dwordx4 v[98:101], v[246:247]
	v_lshl_add_u64 v[246:247], v[176:177], 0, s[98:99]
	flat_load_dwordx4 v[94:97], v[246:247]
	v_lshl_add_u64 v[246:247], v[124:125], 0, s[98:99]
	flat_load_dwordx4 v[90:93], v[246:247]
	v_lshl_add_u64 v[188:189], v[196:197], 0, v[102:103]
	s_and_b64 vcc, exec, s[8:9]
	s_waitcnt vmcnt(0) lgkmcnt(0)
	v_rcp_f32_e32 v232, v232
	v_rcp_f32_e32 v233, v233
	v_rcp_f32_e32 v234, v234
	v_rcp_f32_e32 v235, v235
	v_rcp_f32_e32 v240, v240
	v_rcp_f32_e32 v241, v241
	v_rcp_f32_e32 v242, v242
	v_rcp_f32_e32 v243, v243
	s_nop 0
	v_lshlrev_b32_e32 v190, 16, v182
	v_and_b32_e32 v191, 0xffff0000, v182
	v_lshlrev_b32_e32 v182, 16, v183
	v_and_b32_e32 v183, 0xffff0000, v183
	v_lshlrev_b32_e32 v192, 16, v184
	v_and_b32_e32 v193, 0xffff0000, v184
	v_lshlrev_b32_e32 v184, 16, v185
	v_and_b32_e32 v185, 0xffff0000, v185
	v_pk_mul_f32 v[182:183], v[182:183], v[234:235]
	v_pk_fma_f32 v[64:65], v[64:65], v[88:89], v[182:183]
	v_pk_mul_f32 v[190:191], v[190:191], v[232:233]
	v_pk_fma_f32 v[62:63], v[62:63], v[86:87], v[190:191]
	v_pk_mul_f32 v[192:193], v[192:193], v[240:241]
	v_pk_fma_f32 v[58:59], v[58:59], v[82:83], v[192:193]
	v_pk_mul_f32 v[184:185], v[184:185], v[242:243]
	v_pk_fma_f32 v[60:61], v[60:61], v[84:85], v[184:185]
	v_cvt_pk_bf16_f32 v182, v62, v63
	v_cvt_pk_bf16_f32 v183, v64, v65
	v_cvt_pk_bf16_f32 v184, v58, v59
	s_nop 0
	v_cvt_pk_bf16_f32 v185, v60, v61
	flat_store_dwordx4 v[186:187], v[182:185]
	s_cbranch_vccnz .LBB0_1278
	s_nop 0
	v_pk_mul_f32 v[184:185], v[76:77], v[64:65]
	v_pk_mul_f32 v[182:183], v[74:75], v[62:63]
	v_pk_mul_f32 v[186:187], v[72:73], v[60:61]
	v_pk_mul_f32 v[190:191], v[70:71], v[58:59]
	v_cvt_pk_bf16_f32 v182, v182, v183
	v_cvt_pk_bf16_f32 v183, v184, v185
	s_nop 0
	v_cvt_pk_bf16_f32 v184, v190, v191
	v_cvt_pk_bf16_f32 v185, v186, v187
	v_lshl_add_u64 v[186:187], v[188:189], 1, s[18:19]
	flat_store_dwordx4 v[186:187], v[182:185]

.LBB0_1280:
	s_nop 1
	v_lshlrev_b32_e32 v182, 16, v98
	v_and_b32_e32 v183, 0xffff0000, v98
	v_lshlrev_b32_e32 v184, 16, v99
	v_and_b32_e32 v185, 0xffff0000, v99
	v_lshlrev_b32_e32 v186, 16, v100
	v_and_b32_e32 v187, 0xffff0000, v100
	v_lshlrev_b32_e32 v100, 16, v101
	v_and_b32_e32 v101, 0xffff0000, v101
	v_lshl_add_u64 v[98:99], v[198:199], 0, v[102:103]
	v_pk_mul_f32 v[184:185], v[184:185], v[234:235]
	v_pk_fma_f32 v[56:57], v[56:57], v[88:89], v[184:185]
	v_pk_mul_f32 v[182:183], v[182:183], v[232:233]
	v_pk_fma_f32 v[54:55], v[54:55], v[86:87], v[182:183]
	v_pk_mul_f32 v[186:187], v[186:187], v[240:241]
	v_pk_fma_f32 v[50:51], v[50:51], v[82:83], v[186:187]
	v_pk_mul_f32 v[100:101], v[100:101], v[242:243]
	v_pk_fma_f32 v[52:53], v[52:53], v[84:85], v[100:101]
	s_and_b64 vcc, exec, s[8:9]
	v_cvt_pk_bf16_f32 v182, v54, v55
	v_cvt_pk_bf16_f32 v183, v56, v57
	v_cvt_pk_bf16_f32 v184, v50, v51
	v_cvt_pk_bf16_f32 v185, v52, v53
	flat_store_dwordx4 v[178:179], v[182:185]
	s_cbranch_vccnz .LBB0_1282
	v_pk_mul_f32 v[100:101], v[76:77], v[56:57]
	v_pk_mul_f32 v[178:179], v[74:75], v[54:55]
	v_pk_mul_f32 v[184:185], v[70:71], v[50:51]
	v_cvt_pk_bf16_f32 v182, v178, v179
	v_cvt_pk_bf16_f32 v183, v100, v101
	v_lshl_add_u64 v[100:101], v[98:99], 1, s[18:19]
	v_pk_mul_f32 v[186:187], v[72:73], v[52:53]
	v_cvt_pk_bf16_f32 v184, v184, v185
	s_nop 0
	v_cvt_pk_bf16_f32 v185, v186, v187
	flat_store_dwordx4 v[100:101], v[182:185]

.LBB0_1284:
	v_lshlrev_b32_e32 v100, 16, v94
	v_and_b32_e32 v101, 0xffff0000, v94
	v_lshlrev_b32_e32 v94, 16, v95
	v_and_b32_e32 v95, 0xffff0000, v95
	v_lshlrev_b32_e32 v178, 16, v96
	v_and_b32_e32 v179, 0xffff0000, v96
	v_lshlrev_b32_e32 v96, 16, v97
	v_and_b32_e32 v97, 0xffff0000, v97
	v_lshl_add_u64 v[98:99], v[200:201], 0, v[102:103]
	v_pk_mul_f32 v[94:95], v[94:95], v[234:235]
	v_pk_fma_f32 v[48:49], v[48:49], v[88:89], v[94:95]
	v_pk_mul_f32 v[100:101], v[100:101], v[232:233]
	v_pk_fma_f32 v[46:47], v[46:47], v[86:87], v[100:101]
	v_pk_mul_f32 v[178:179], v[178:179], v[240:241]
	v_pk_fma_f32 v[94:95], v[42:43], v[82:83], v[178:179]
	v_pk_mul_f32 v[96:97], v[96:97], v[242:243]
	v_pk_fma_f32 v[96:97], v[44:45], v[84:85], v[96:97]
	s_and_b64 vcc, exec, s[8:9]
	v_cvt_pk_bf16_f32 v42, v46, v47
	v_cvt_pk_bf16_f32 v43, v48, v49
	v_cvt_pk_bf16_f32 v44, v94, v95
	v_cvt_pk_bf16_f32 v45, v96, v97
	flat_store_dwordx4 v[176:177], v[42:45]
	s_cbranch_vccnz .LBB0_1286
	s_nop 0
	v_pk_mul_f32 v[44:45], v[76:77], v[48:49]
	v_pk_mul_f32 v[42:43], v[74:75], v[46:47]
	v_pk_mul_f32 v[100:101], v[72:73], v[96:97]
	v_pk_mul_f32 v[176:177], v[70:71], v[94:95]
	v_cvt_pk_bf16_f32 v42, v42, v43
	v_cvt_pk_bf16_f32 v43, v44, v45
	s_nop 0
	v_cvt_pk_bf16_f32 v44, v176, v177
	v_cvt_pk_bf16_f32 v45, v100, v101
	v_lshl_add_u64 v[100:101], v[98:99], 1, s[18:19]
	flat_store_dwordx4 v[100:101], v[42:45]

.LBB0_1288:
	s_nop 1
	v_lshlrev_b32_e32 v44, 16, v90
	v_and_b32_e32 v45, 0xffff0000, v90
	v_lshlrev_b32_e32 v90, 16, v91
	v_and_b32_e32 v91, 0xffff0000, v91
	v_lshlrev_b32_e32 v98, 16, v92
	v_and_b32_e32 v99, 0xffff0000, v92
	v_lshlrev_b32_e32 v100, 16, v93
	v_and_b32_e32 v101, 0xffff0000, v93
	v_lshl_add_u64 v[42:43], v[202:203], 0, v[102:103]
	v_pk_mul_f32 v[90:91], v[90:91], v[234:235]
	v_pk_fma_f32 v[90:91], v[40:41], v[88:89], v[90:91]
	v_pk_mul_f32 v[44:45], v[44:45], v[232:233]
	v_pk_fma_f32 v[92:93], v[38:39], v[86:87], v[44:45]
	v_pk_mul_f32 v[98:99], v[98:99], v[240:241]
	v_pk_fma_f32 v[98:99], v[34:35], v[82:83], v[98:99]
	v_pk_mul_f32 v[100:101], v[100:101], v[242:243]
	v_pk_fma_f32 v[100:101], v[36:37], v[84:85], v[100:101]
	s_and_b64 vcc, exec, s[8:9]
	v_cvt_pk_bf16_f32 v34, v92, v93
	v_cvt_pk_bf16_f32 v35, v90, v91
	v_cvt_pk_bf16_f32 v36, v98, v99
	v_cvt_pk_bf16_f32 v37, v100, v101
	flat_store_dwordx4 v[124:125], v[34:37]
	s_cbranch_vccnz .LBB0_1290
	s_nop 0
	v_pk_mul_f32 v[36:37], v[76:77], v[90:91]
	v_pk_mul_f32 v[34:35], v[74:75], v[92:93]
	v_pk_mul_f32 v[38:39], v[72:73], v[100:101]
	v_pk_mul_f32 v[40:41], v[70:71], v[98:99]
	v_cvt_pk_bf16_f32 v34, v34, v35
	v_cvt_pk_bf16_f32 v35, v36, v37
	s_nop 0
	v_cvt_pk_bf16_f32 v36, v40, v41
	v_cvt_pk_bf16_f32 v37, v38, v39
	v_lshl_add_u64 v[38:39], v[42:43], 1, s[18:19]
	flat_store_dwordx4 v[38:39], v[34:37]

.LBB0_1292:
	s_nop 1
	v_lshl_add_u64 v[34:35], s[12:13], 0, v[204:205]
	v_lshl_add_u64 v[186:187], v[34:35], 0, v[104:105]
	v_lshl_add_u64 v[34:35], s[12:13], 0, v[206:207]
	v_lshl_add_u64 v[246:247], v[186:187], 0, s[98:99]
	flat_load_dwordx4 v[182:185], v[246:247]
	v_lshl_add_u64 v[36:37], s[12:13], 0, v[208:209]
	v_lshl_add_u64 v[38:39], s[12:13], 0, v[210:211]
	v_lshl_add_u64 v[176:177], v[34:35], 0, v[104:105]
	v_lshl_add_u64 v[124:125], v[36:37], 0, v[104:105]
	v_lshl_add_u64 v[104:105], v[38:39], 0, v[104:105]
	v_lshl_add_u64 v[246:247], v[176:177], 0, s[98:99]
	flat_load_dwordx4 v[42:45], v[246:247]
	v_lshl_add_u64 v[246:247], v[124:125], 0, s[98:99]
	flat_load_dwordx4 v[38:41], v[246:247]
	v_lshl_add_u64 v[246:247], v[104:105], 0, s[98:99]
	flat_load_dwordx4 v[34:37], v[246:247]
	v_lshl_add_u64 v[178:179], v[212:213], 0, v[102:103]
	s_and_b64 vcc, exec, s[8:9]
	s_waitcnt vmcnt(0) lgkmcnt(0)
	v_lshlrev_b32_e32 v188, 16, v182
	v_and_b32_e32 v189, 0xffff0000, v182
	v_lshlrev_b32_e32 v182, 16, v183
	v_and_b32_e32 v183, 0xffff0000, v183
	v_lshlrev_b32_e32 v190, 16, v184
	v_and_b32_e32 v191, 0xffff0000, v184
	v_lshlrev_b32_e32 v184, 16, v185
	v_and_b32_e32 v185, 0xffff0000, v185
	v_pk_mul_f32 v[182:183], v[182:183], v[234:235]
	v_pk_fma_f32 v[32:33], v[32:33], v[88:89], v[182:183]
	v_pk_mul_f32 v[188:189], v[188:189], v[232:233]
	v_pk_fma_f32 v[30:31], v[30:31], v[86:87], v[188:189]
	v_pk_mul_f32 v[190:191], v[190:191], v[240:241]
	v_pk_fma_f32 v[26:27], v[26:27], v[82:83], v[190:191]
	v_pk_mul_f32 v[184:185], v[184:185], v[242:243]
	v_pk_fma_f32 v[28:29], v[28:29], v[84:85], v[184:185]
	v_cvt_pk_bf16_f32 v182, v30, v31
	v_cvt_pk_bf16_f32 v183, v32, v33
	v_cvt_pk_bf16_f32 v184, v26, v27
	s_nop 0
	v_cvt_pk_bf16_f32 v185, v28, v29
	flat_store_dwordx4 v[186:187], v[182:185]
	s_cbranch_vccnz .LBB0_1294
	s_nop 0
	v_pk_mul_f32 v[184:185], v[76:77], v[32:33]
	v_pk_mul_f32 v[182:183], v[74:75], v[30:31]
	v_pk_mul_f32 v[186:187], v[72:73], v[28:29]
	v_pk_mul_f32 v[188:189], v[70:71], v[26:27]
	v_cvt_pk_bf16_f32 v182, v182, v183
	v_cvt_pk_bf16_f32 v183, v184, v185
	s_nop 0
	v_cvt_pk_bf16_f32 v184, v188, v189
	v_cvt_pk_bf16_f32 v185, v186, v187
	v_lshl_add_u64 v[186:187], v[178:179], 1, s[18:19]
	flat_store_dwordx4 v[186:187], v[182:185]

.LBB0_1296:
	v_lshlrev_b32_e32 v178, 16, v42
	v_and_b32_e32 v179, 0xffff0000, v42
	v_lshlrev_b32_e32 v182, 16, v43
	v_and_b32_e32 v183, 0xffff0000, v43
	v_lshlrev_b32_e32 v184, 16, v44
	v_and_b32_e32 v185, 0xffff0000, v44
	v_lshlrev_b32_e32 v44, 16, v45
	v_and_b32_e32 v45, 0xffff0000, v45
	v_lshl_add_u64 v[42:43], v[214:215], 0, v[102:103]
	v_pk_mul_f32 v[182:183], v[182:183], v[234:235]
	v_pk_fma_f32 v[24:25], v[24:25], v[88:89], v[182:183]
	v_pk_mul_f32 v[178:179], v[178:179], v[232:233]
	v_pk_fma_f32 v[22:23], v[22:23], v[86:87], v[178:179]
	v_pk_mul_f32 v[184:185], v[184:185], v[240:241]
	v_pk_fma_f32 v[18:19], v[18:19], v[82:83], v[184:185]
	v_pk_mul_f32 v[44:45], v[44:45], v[242:243]
	v_pk_fma_f32 v[20:21], v[20:21], v[84:85], v[44:45]
	s_and_b64 vcc, exec, s[8:9]
	v_cvt_pk_bf16_f32 v182, v22, v23
	v_cvt_pk_bf16_f32 v183, v24, v25
	v_cvt_pk_bf16_f32 v184, v18, v19
	v_cvt_pk_bf16_f32 v185, v20, v21
	flat_store_dwordx4 v[176:177], v[182:185]
	s_cbranch_vccnz .LBB0_1298
	v_pk_mul_f32 v[44:45], v[76:77], v[24:25]
	v_pk_mul_f32 v[176:177], v[74:75], v[22:23]
	v_pk_mul_f32 v[178:179], v[70:71], v[18:19]
	v_cvt_pk_bf16_f32 v176, v176, v177
	v_cvt_pk_bf16_f32 v177, v44, v45
	v_lshl_add_u64 v[44:45], v[42:43], 1, s[18:19]
	v_pk_mul_f32 v[182:183], v[72:73], v[20:21]
	v_cvt_pk_bf16_f32 v178, v178, v179
	s_nop 0
	v_cvt_pk_bf16_f32 v179, v182, v183
	flat_store_dwordx4 v[44:45], v[176:179]

.LBB0_1300:
	v_lshlrev_b32_e32 v42, 16, v38
	v_and_b32_e32 v43, 0xffff0000, v38
	v_lshlrev_b32_e32 v44, 16, v39
	v_and_b32_e32 v45, 0xffff0000, v39
	v_lshlrev_b32_e32 v176, 16, v40
	v_and_b32_e32 v177, 0xffff0000, v40
	v_lshlrev_b32_e32 v40, 16, v41
	v_and_b32_e32 v41, 0xffff0000, v41
	v_lshl_add_u64 v[38:39], v[216:217], 0, v[102:103]
	v_pk_mul_f32 v[44:45], v[44:45], v[234:235]
	v_pk_fma_f32 v[16:17], v[16:17], v[88:89], v[44:45]
	v_pk_mul_f32 v[42:43], v[42:43], v[232:233]
	v_pk_fma_f32 v[14:15], v[14:15], v[86:87], v[42:43]
	v_pk_mul_f32 v[176:177], v[176:177], v[240:241]
	v_pk_fma_f32 v[10:11], v[10:11], v[82:83], v[176:177]
	v_pk_mul_f32 v[40:41], v[40:41], v[242:243]
	v_pk_fma_f32 v[12:13], v[12:13], v[84:85], v[40:41]
	s_and_b64 vcc, exec, s[8:9]
	v_cvt_pk_bf16_f32 v40, v14, v15
	v_cvt_pk_bf16_f32 v41, v16, v17
	v_cvt_pk_bf16_f32 v42, v10, v11
	v_cvt_pk_bf16_f32 v43, v12, v13
	flat_store_dwordx4 v[124:125], v[40:43]
	s_cbranch_vccnz .LBB0_1302
	s_nop 0
	v_pk_mul_f32 v[42:43], v[76:77], v[16:17]
	v_pk_mul_f32 v[40:41], v[74:75], v[14:15]
	v_pk_mul_f32 v[44:45], v[72:73], v[12:13]
	v_pk_mul_f32 v[124:125], v[70:71], v[10:11]
	v_cvt_pk_bf16_f32 v40, v40, v41
	v_cvt_pk_bf16_f32 v41, v42, v43
	s_nop 0
	v_cvt_pk_bf16_f32 v42, v124, v125
	v_cvt_pk_bf16_f32 v43, v44, v45
	v_lshl_add_u64 v[44:45], v[38:39], 1, s[18:19]
	flat_store_dwordx4 v[44:45], v[40:43]

.LBB0_1304:
	v_lshlrev_b32_e32 v38, 16, v34
	v_and_b32_e32 v39, 0xffff0000, v34
	v_lshlrev_b32_e32 v40, 16, v35
	v_and_b32_e32 v41, 0xffff0000, v35
	v_lshlrev_b32_e32 v42, 16, v36
	v_and_b32_e32 v43, 0xffff0000, v36
	v_lshlrev_b32_e32 v36, 16, v37
	v_and_b32_e32 v37, 0xffff0000, v37
	v_lshl_add_u64 v[34:35], v[122:123], 0, v[102:103]
	v_pk_mul_f32 v[40:41], v[40:41], v[234:235]
	v_pk_fma_f32 v[8:9], v[8:9], v[88:89], v[40:41]
	v_pk_mul_f32 v[38:39], v[38:39], v[232:233]
	v_pk_fma_f32 v[6:7], v[6:7], v[86:87], v[38:39]
	v_pk_mul_f32 v[42:43], v[42:43], v[240:241]
	v_pk_fma_f32 v[2:3], v[2:3], v[82:83], v[42:43]
	v_pk_mul_f32 v[36:37], v[36:37], v[242:243]
	v_pk_fma_f32 v[4:5], v[4:5], v[84:85], v[36:37]
	s_and_b64 vcc, exec, s[8:9]
	v_cvt_pk_bf16_f32 v36, v6, v7
	v_cvt_pk_bf16_f32 v37, v8, v9
	v_cvt_pk_bf16_f32 v38, v2, v3
	v_cvt_pk_bf16_f32 v39, v4, v5
	flat_store_dwordx4 v[104:105], v[36:39]
	s_cbranch_vccnz .LBB0_1324
	s_nop 0
	v_pk_mul_f32 v[38:39], v[76:77], v[8:9]
	v_pk_mul_f32 v[36:37], v[74:75], v[6:7]
	v_pk_mul_f32 v[40:41], v[72:73], v[4:5]
	v_pk_mul_f32 v[42:43], v[70:71], v[2:3]
	v_cvt_pk_bf16_f32 v36, v36, v37
	v_cvt_pk_bf16_f32 v37, v38, v39
	s_nop 0
	v_cvt_pk_bf16_f32 v38, v42, v43
	v_cvt_pk_bf16_f32 v39, v40, v41
	v_lshl_add_u64 v[40:41], v[34:35], 1, s[18:19]
	flat_store_dwordx4 v[40:41], v[36:39]
	s_and_b64 vcc, exec, s[6:7]
	s_cbranch_vccz .LBB0_1325
